# v44 + up K-loop last iteration peeled: HALO rows prefetched into free VGPRs there, epilogue sites copy instead of loading
# baseline (speedup 1.0000x reference)
; #define PG8_STAGE(bufoff, gbase, voff) do { _Pragma("unroll") for (int _i = 0; _i < 2; ++_i) glds16_s((gbase), (voff)[_i], ldsb + (unsigned)((bufoff) + _i * 8192)); } while (0)
; #define PG8_LDA(dst, b, h) do { _Pragma("unroll") for (int m = 0; m < 4; ++m) _Pragma("unroll") for (int k = 0; k < 2; ++k) dst[m][k] = *(const LAS h16x8*)(lds + PG8_SA(b, h) + aoff + m * 2048 + k * 1024); } while (0)
; #define PG8_LDB(dst, b, h) do { _Pragma("unroll") for (int n = 0; n < 2; ++n) _Pragma("unroll") for (int k = 0; k < 2; ++k) dst[n][k] = *(const LAS h16x8*)(lds + PG8_SB(b, h) + boff + n * 2048 + k * 1024); } while (0)
; #define PG8_MMA(ai, bj, At, Bt) do { __builtin_amdgcn_s_setprio(1); _Pragma("unroll") for (int m = 0; m < 4; ++m) _Pragma("unroll") for (int n = 0; n < 2; ++n) _Pragma("unroll") for (int k = 0; k < 2; ++k) \
;         acc[ai][bj][m][n] = mma_step<I8>(Bt[n][k], At[m][k], acc[ai][bj][m][n]); __builtin_amdgcn_s_setprio(0); } while (0)
; #define PG8_WAIT_V(n) asm volatile("s_waitcnt vmcnt(" #n ")" ::: "memory")
; #define PG8_WAIT_L(n) asm volatile("s_waitcnt lgkmcnt(" #n ")" ::: "memory")
; #define PG8_BAR __builtin_amdgcn_s_barrier()
; #define PG8_SCHED __builtin_amdgcn_sched_barrier(0)
; template <class Prob, class Epi, bool I8 = false, bool ALIGN_EPI = true, bool SP2 = true>
; __device__ __forceinline__ void gemm_phase(LAS unsigned char* lds, int wave, const Prob& P, const Epi& E) {
;     ...
;             PG8_LDB(B0, 0, 0); PG8_LDB(B1, 0, 1); PG8_SCHED; PG8_LDA(At, 0, 0); PG8_STAGE(PG8_SA(1, 1), a1 + hstepA, voffA);
;             PG8_WAIT_V(8); PG8_WAIT_L(0); PG8_BAR; PG8_MMA(0, 0, At, B0); PG8_MMA(0, 1, At, B1); PG8_BAR; PG8_SCHED;
;             PG8_LDA(At, 0, 1); PG8_STAGE(PG8_SB(0, 0), b2, voffB); PG8_STAGE(PG8_SB(0, 1), b2 + hstepB, voffB); PG8_STAGE(PG8_SA(0, 0), a2, voffA);
;             PG8_WAIT_V(8); PG8_WAIT_L(0); PG8_BAR; PG8_MMA(1, 0, At, B0); PG8_MMA(1, 1, At, B1); PG8_BAR; PG8_SCHED;
;             PG8_LDB(B0, 1, 0); PG8_LDB(B1, 1, 1); PG8_SCHED; PG8_LDA(At, 1, 0); PG8_STAGE(PG8_SA(0, 1), a2 + hstepA, voffA);
;             PG8_WAIT_V(8); PG8_WAIT_L(0); PG8_BAR; PG8_MMA(0, 0, At, B0); PG8_MMA(0, 1, At, B1); PG8_BAR; PG8_SCHED;
.LBB0_1065:
	v_add_u32_e32 v124, 0x10000, v210
	v_add_u32_e32 v140, 0x14000, v210
	ds_read_b128 v[104:107], v124
	ds_read_b128 v[112:115], v124 offset:1024
	ds_read_b128 v[120:123], v124 offset:2048
	ds_read_b128 v[124:127], v124 offset:3072
	ds_read_b128 v[128:131], v140
	ds_read_b128 v[132:135], v140 offset:1024
	ds_read_b128 v[136:139], v140 offset:2048
	ds_read_b128 v[140:143], v140 offset:3072
	s_cmp_eq_u32 s4, 12
	s_cselect_b32 s62, s96, vcc_lo
	s_cselect_b32 s63, s51, vcc_hi
	s_cselect_b32 s68, s97, s0
	s_cselect_b32 s69, s49, s1
	s_add_u32 s60, s62, 0x80
	s_addc_u32 s61, s63, 0
	ds_read_b128 v[144:147], v211
	ds_read_b128 v[164:167], v211 offset:1024
	ds_read_b128 v[168:171], v211 offset:2048
	ds_read_b128 v[172:175], v211 offset:3072
	ds_read_b128 v[176:179], v211 offset:4096
	ds_read_b128 v[180:183], v211 offset:5120
	ds_read_b128 v[184:187], v211 offset:6144
	ds_read_b128 v[188:191], v211 offset:7168
	s_mov_b32 s5, m0
	s_mov_b32 m0, s90
	s_nop 0
	global_load_lds_dwordx4 v250, s[44:45]
	s_mov_b32 m0, s5
	s_nop 0
	s_mov_b32 s5, m0
	s_mov_b32 m0, s92
	s_nop 0
	global_load_lds_dwordx4 v247, s[44:45]
	s_mov_b32 m0, s5
	s_waitcnt vmcnt(8)
	s_waitcnt lgkmcnt(0)
	s_barrier
	s_setprio 1
	s_waitcnt lgkmcnt(7)
	v_mfma_i32_16x16x64_i8 v[160:163], v[104:107], v[144:147], v[160:163]
	v_mfma_i32_16x16x64_i8 v[152:155], v[120:123], v[144:147], v[152:155]
	s_waitcnt lgkmcnt(5)
	v_mfma_i32_16x16x64_i8 v[52:55], v[104:107], v[168:171], v[52:55]
	v_mfma_i32_16x16x64_i8 v[80:83], v[120:123], v[168:171], v[80:83]
	s_waitcnt lgkmcnt(3)
	v_mfma_i32_16x16x64_i8 v[48:51], v[104:107], v[176:179], v[48:51]
	v_mfma_i32_16x16x64_i8 v[72:75], v[120:123], v[176:179], v[72:75]
	s_waitcnt lgkmcnt(1)
	v_mfma_i32_16x16x64_i8 v[44:47], v[104:107], v[184:187], v[44:47]
	v_mfma_i32_16x16x64_i8 v[68:71], v[120:123], v[184:187], v[68:71]
	v_mfma_i32_16x16x64_i8 v[160:163], v[112:115], v[164:167], v[160:163]
	v_mfma_i32_16x16x64_i8 v[152:155], v[124:127], v[164:167], v[152:155]
	v_mfma_i32_16x16x64_i8 v[52:55], v[112:115], v[172:175], v[52:55]
	v_mfma_i32_16x16x64_i8 v[80:83], v[124:127], v[172:175], v[80:83]
	v_mfma_i32_16x16x64_i8 v[48:51], v[112:115], v[180:183], v[48:51]
	v_mfma_i32_16x16x64_i8 v[72:75], v[124:127], v[180:183], v[72:75]
	s_waitcnt lgkmcnt(0)
	v_mfma_i32_16x16x64_i8 v[44:47], v[112:115], v[188:191], v[44:47]
	v_mfma_i32_16x16x64_i8 v[68:71], v[124:127], v[188:191], v[68:71]
	s_setprio 0
	s_setprio 1
	v_mfma_i32_16x16x64_i8 v[116:119], v[128:131], v[144:147], v[116:119]
	v_mfma_i32_16x16x64_i8 v[28:31], v[136:139], v[144:147], v[28:31]
	v_mfma_i32_16x16x64_i8 v[100:103], v[128:131], v[168:171], v[100:103]
	v_mfma_i32_16x16x64_i8 v[24:27], v[136:139], v[168:171], v[24:27]
	v_mfma_i32_16x16x64_i8 v[96:99], v[128:131], v[176:179], v[96:99]
	v_mfma_i32_16x16x64_i8 v[20:23], v[136:139], v[176:179], v[20:23]
	v_mfma_i32_16x16x64_i8 v[92:95], v[128:131], v[184:187], v[92:95]
	v_mfma_i32_16x16x64_i8 v[16:19], v[136:139], v[184:187], v[16:19]
	v_mfma_i32_16x16x64_i8 v[116:119], v[132:135], v[164:167], v[116:119]
	v_mfma_i32_16x16x64_i8 v[28:31], v[140:143], v[164:167], v[28:31]
	v_mfma_i32_16x16x64_i8 v[100:103], v[132:135], v[172:175], v[100:103]
	v_mfma_i32_16x16x64_i8 v[24:27], v[140:143], v[172:175], v[24:27]
	v_mfma_i32_16x16x64_i8 v[96:99], v[132:135], v[180:183], v[96:99]
	v_mfma_i32_16x16x64_i8 v[20:23], v[140:143], v[180:183], v[20:23]
	v_mfma_i32_16x16x64_i8 v[92:95], v[132:135], v[188:191], v[92:95]
	v_mfma_i32_16x16x64_i8 v[16:19], v[140:143], v[188:191], v[16:19]
	s_setprio 0
	s_barrier
	ds_read_b128 v[144:147], v211 offset:16384
	ds_read_b128 v[164:167], v211 offset:17408
	ds_read_b128 v[168:171], v211 offset:18432
	ds_read_b128 v[172:175], v211 offset:19456
	ds_read_b128 v[176:179], v211 offset:20480
	ds_read_b128 v[180:183], v211 offset:21504
	ds_read_b128 v[184:187], v211 offset:22528
	ds_read_b128 v[188:191], v211 offset:23552
	s_mov_b32 s5, m0
	s_mov_b32 m0, s73
	s_nop 0
	global_load_lds_dwordx4 v217, s[68:69]
	s_mov_b32 m0, s5
	s_add_u32 s6, s68, 0x40000
	s_mov_b32 s5, m0
	s_mov_b32 m0, s74
	s_nop 0
	global_load_lds_dwordx4 v248, s[68:69]
	s_mov_b32 m0, s5
	s_addc_u32 s7, s69, 0
	s_mov_b32 s5, m0
	s_mov_b32 m0, s75
	s_nop 0
	global_load_lds_dwordx4 v217, s[6:7]
	s_mov_b32 m0, s5
	s_nop 0
	s_mov_b32 s5, m0
	s_mov_b32 m0, s80
	s_nop 0
	global_load_lds_dwordx4 v248, s[6:7]
	s_mov_b32 m0, s5
	s_nop 0
	s_mov_b32 s5, m0
	s_mov_b32 m0, s72
	s_nop 0
	global_load_lds_dwordx4 v250, s[62:63]
	s_mov_b32 m0, s5
	s_nop 0
	s_mov_b32 s5, m0
	s_mov_b32 m0, s81
	s_nop 0
	global_load_lds_dwordx4 v247, s[62:63]
	s_mov_b32 m0, s5
	s_waitcnt vmcnt(8)
	s_waitcnt lgkmcnt(0)
	s_barrier
; #define PG8_STAGE(bufoff, gbase, voff) do { _Pragma("unroll") for (int _i = 0; _i < 2; ++_i) glds16_s((gbase), (voff)[_i], ldsb + (unsigned)((bufoff) + _i * 8192)); } while (0)
; #define PG8_LDA(dst, b, h) do { _Pragma("unroll") for (int m = 0; m < 4; ++m) _Pragma("unroll") for (int k = 0; k < 2; ++k) dst[m][k] = *(const LAS h16x8*)(lds + PG8_SA(b, h) + aoff + m * 2048 + k * 1024); } while (0)
; #define PG8_LDB(dst, b, h) do { _Pragma("unroll") for (int n = 0; n < 2; ++n) _Pragma("unroll") for (int k = 0; k < 2; ++k) dst[n][k] = *(const LAS h16x8*)(lds + PG8_SB(b, h) + boff + n * 2048 + k * 1024); } while (0)
; #define PG8_MMA(ai, bj, At, Bt) do { __builtin_amdgcn_s_setprio(1); _Pragma("unroll") for (int m = 0; m < 4; ++m) _Pragma("unroll") for (int n = 0; n < 2; ++n) _Pragma("unroll") for (int k = 0; k < 2; ++k) \
;         acc[ai][bj][m][n] = mma_step<I8>(Bt[n][k], At[m][k], acc[ai][bj][m][n]); __builtin_amdgcn_s_setprio(0); } while (0)
; #define PG8_WAIT_V(n) asm volatile("s_waitcnt vmcnt(" #n ")" ::: "memory")
; #define PG8_WAIT_L(n) asm volatile("s_waitcnt lgkmcnt(" #n ")" ::: "memory")
; #define PG8_BAR __builtin_amdgcn_s_barrier()
; #define PG8_SCHED __builtin_amdgcn_sched_barrier(0)
; template <class Prob, class Epi, bool I8 = false, bool ALIGN_EPI = true, bool SP2 = true>
; __device__ __forceinline__ void gemm_phase(LAS unsigned char* lds, int wave, const Prob& P, const Epi& E) {
;     ...
;             PG8_WAIT_V(8); PG8_WAIT_L(0); PG8_BAR; PG8_MMA(0, 0, At, B0); PG8_MMA(0, 1, At, B1); PG8_BAR; PG8_SCHED;
;             PG8_LDA(At, 0, 1); PG8_STAGE(PG8_SB(0, 0), b2, voffB); PG8_STAGE(PG8_SB(0, 1), b2 + hstepB, voffB); PG8_STAGE(PG8_SA(0, 0), a2, voffA);
;             PG8_WAIT_V(8); PG8_WAIT_L(0); PG8_BAR; PG8_MMA(1, 0, At, B0); PG8_MMA(1, 1, At, B1); PG8_BAR; PG8_SCHED;
;             PG8_LDB(B0, 1, 0); PG8_LDB(B1, 1, 1); PG8_SCHED; PG8_LDA(At, 1, 0); PG8_STAGE(PG8_SA(0, 1), a2 + hstepA, voffA);
;             PG8_WAIT_V(8); PG8_WAIT_L(0); PG8_BAR; PG8_MMA(0, 0, At, B0); PG8_MMA(0, 1, At, B1); PG8_BAR; PG8_SCHED;
	s_setprio 1
	s_waitcnt lgkmcnt(7)
	v_mfma_i32_16x16x64_i8 v[40:43], v[104:107], v[144:147], v[40:43]
	v_mfma_i32_16x16x64_i8 v[64:67], v[120:123], v[144:147], v[64:67]
	s_waitcnt lgkmcnt(5)
	v_mfma_i32_16x16x64_i8 v[36:39], v[104:107], v[168:171], v[36:39]
	v_mfma_i32_16x16x64_i8 v[60:63], v[120:123], v[168:171], v[60:63]
	s_waitcnt lgkmcnt(3)
	v_mfma_i32_16x16x64_i8 v[32:35], v[104:107], v[176:179], v[32:35]
	v_mfma_i32_16x16x64_i8 v[56:59], v[120:123], v[176:179], v[56:59]
	s_waitcnt lgkmcnt(1)
	v_mfma_i32_16x16x64_i8 v[104:107], v[104:107], v[184:187], v[156:159]
	v_mfma_i32_16x16x64_i8 v[40:43], v[112:115], v[164:167], v[40:43]
	v_mfma_i32_16x16x64_i8 v[64:67], v[124:127], v[164:167], v[64:67]
	v_mfma_i32_16x16x64_i8 v[36:39], v[112:115], v[172:175], v[36:39]
	v_mfma_i32_16x16x64_i8 v[60:63], v[124:127], v[172:175], v[60:63]
	v_mfma_i32_16x16x64_i8 v[32:35], v[112:115], v[180:183], v[32:35]
	v_mfma_i32_16x16x64_i8 v[56:59], v[124:127], v[180:183], v[56:59]
	s_waitcnt lgkmcnt(0)
	v_mfma_i32_16x16x64_i8 v[104:107], v[112:115], v[188:191], v[104:107]
	v_mfma_i32_16x16x64_i8 v[112:115], v[120:123], v[184:187], v[148:151]
	v_mfma_i32_16x16x64_i8 v[112:115], v[124:127], v[188:191], v[112:115]
	s_setprio 0
	s_setprio 1
	v_mfma_i32_16x16x64_i8 v[88:91], v[128:131], v[144:147], v[88:91]
	v_mfma_i32_16x16x64_i8 v[12:15], v[136:139], v[144:147], v[12:15]
	v_mfma_i32_16x16x64_i8 v[84:87], v[128:131], v[168:171], v[84:87]
	v_mfma_i32_16x16x64_i8 v[8:11], v[136:139], v[168:171], v[8:11]
	v_mfma_i32_16x16x64_i8 v[76:79], v[128:131], v[176:179], v[76:79]
	v_mfma_i32_16x16x64_i8 v[4:7], v[136:139], v[176:179], v[4:7]
	v_mfma_i32_16x16x64_i8 v[108:111], v[128:131], v[184:187], v[108:111]
	v_mfma_i32_16x16x64_i8 v[0:3], v[136:139], v[184:187], v[0:3]
	v_mfma_i32_16x16x64_i8 v[88:91], v[132:135], v[164:167], v[88:91]
	v_mfma_i32_16x16x64_i8 v[12:15], v[140:143], v[164:167], v[12:15]
	v_mfma_i32_16x16x64_i8 v[84:87], v[132:135], v[172:175], v[84:87]
	v_mfma_i32_16x16x64_i8 v[8:11], v[140:143], v[172:175], v[8:11]
	v_mfma_i32_16x16x64_i8 v[76:79], v[132:135], v[180:183], v[76:79]
	v_mfma_i32_16x16x64_i8 v[4:7], v[140:143], v[180:183], v[4:7]
	v_mfma_i32_16x16x64_i8 v[108:111], v[132:135], v[188:191], v[108:111]
	v_mfma_i32_16x16x64_i8 v[0:3], v[140:143], v[188:191], v[0:3]
	s_setprio 0
	s_barrier
	v_add_u32_e32 v132, 0x18000, v210
	v_add_u32_e32 v148, 0x1c000, v210
	ds_read_b128 v[120:123], v132
	ds_read_b128 v[124:127], v132 offset:1024
	ds_read_b128 v[128:131], v132 offset:2048
	ds_read_b128 v[132:135], v132 offset:3072
	ds_read_b128 v[136:139], v148
	ds_read_b128 v[140:143], v148 offset:1024
	ds_read_b128 v[144:147], v148 offset:2048
	ds_read_b128 v[164:167], v148 offset:3072
	ds_read_b128 v[148:151], v211 offset:32768
	ds_read_b128 v[156:159], v211 offset:33792
	ds_read_b128 v[168:171], v211 offset:34816
	ds_read_b128 v[172:175], v211 offset:35840
	ds_read_b128 v[176:179], v211 offset:36864
	ds_read_b128 v[180:183], v211 offset:37888
	ds_read_b128 v[184:187], v211 offset:38912
	ds_read_b128 v[188:191], v211 offset:39936
	s_add_u32 s6, s62, 0x2000
	s_addc_u32 s7, s63, 0
	s_mov_b32 s5, m0
	s_mov_b32 m0, s82
	s_nop 0
	global_load_lds_dwordx4 v250, s[6:7]
	s_mov_b32 m0, s5
	s_nop 0
	s_mov_b32 s5, m0
	s_mov_b32 m0, s83
	s_nop 0
	global_load_lds_dwordx4 v247, s[6:7]
	s_mov_b32 m0, s5
	s_waitcnt vmcnt(8)
	s_waitcnt lgkmcnt(0)
	s_barrier
	s_setprio 1
	s_waitcnt lgkmcnt(7)
	v_mfma_i32_16x16x64_i8 v[160:163], v[120:123], v[148:151], v[160:163]
	v_mfma_i32_16x16x64_i8 v[152:155], v[128:131], v[148:151], v[152:155]
	s_waitcnt lgkmcnt(5)
	v_mfma_i32_16x16x64_i8 v[52:55], v[120:123], v[168:171], v[52:55]
	v_mfma_i32_16x16x64_i8 v[80:83], v[128:131], v[168:171], v[80:83]
	s_waitcnt lgkmcnt(3)
	v_mfma_i32_16x16x64_i8 v[48:51], v[120:123], v[176:179], v[48:51]
	v_mfma_i32_16x16x64_i8 v[72:75], v[128:131], v[176:179], v[72:75]
	s_waitcnt lgkmcnt(1)
	v_mfma_i32_16x16x64_i8 v[44:47], v[120:123], v[184:187], v[44:47]
	v_mfma_i32_16x16x64_i8 v[68:71], v[128:131], v[184:187], v[68:71]
	v_mfma_i32_16x16x64_i8 v[160:163], v[124:127], v[156:159], v[160:163]
	v_mfma_i32_16x16x64_i8 v[152:155], v[132:135], v[156:159], v[152:155]
	v_mfma_i32_16x16x64_i8 v[52:55], v[124:127], v[172:175], v[52:55]
	v_mfma_i32_16x16x64_i8 v[80:83], v[132:135], v[172:175], v[80:83]
	v_mfma_i32_16x16x64_i8 v[48:51], v[124:127], v[180:183], v[48:51]
	v_mfma_i32_16x16x64_i8 v[72:75], v[132:135], v[180:183], v[72:75]
	s_waitcnt lgkmcnt(0)
	v_mfma_i32_16x16x64_i8 v[44:47], v[124:127], v[188:191], v[44:47]
	v_mfma_i32_16x16x64_i8 v[68:71], v[132:135], v[188:191], v[68:71]
	s_setprio 0
	s_setprio 1
	v_mfma_i32_16x16x64_i8 v[116:119], v[136:139], v[148:151], v[116:119]
	v_mfma_i32_16x16x64_i8 v[28:31], v[144:147], v[148:151], v[28:31]
	v_mfma_i32_16x16x64_i8 v[100:103], v[136:139], v[168:171], v[100:103]
	v_mfma_i32_16x16x64_i8 v[24:27], v[144:147], v[168:171], v[24:27]
	v_mfma_i32_16x16x64_i8 v[96:99], v[136:139], v[176:179], v[96:99]
	v_mfma_i32_16x16x64_i8 v[20:23], v[144:147], v[176:179], v[20:23]
	v_mfma_i32_16x16x64_i8 v[92:95], v[136:139], v[184:187], v[92:95]
	v_mfma_i32_16x16x64_i8 v[16:19], v[144:147], v[184:187], v[16:19]
	v_mfma_i32_16x16x64_i8 v[116:119], v[140:143], v[156:159], v[116:119]
	v_mfma_i32_16x16x64_i8 v[28:31], v[164:167], v[156:159], v[28:31]
	v_mfma_i32_16x16x64_i8 v[100:103], v[140:143], v[172:175], v[100:103]
	v_mfma_i32_16x16x64_i8 v[24:27], v[164:167], v[172:175], v[24:27]
	v_mfma_i32_16x16x64_i8 v[96:99], v[140:143], v[180:183], v[96:99]
	v_mfma_i32_16x16x64_i8 v[20:23], v[164:167], v[180:183], v[20:23]
	v_mfma_i32_16x16x64_i8 v[92:95], v[140:143], v[188:191], v[92:95]
	v_mfma_i32_16x16x64_i8 v[16:19], v[164:167], v[188:191], v[16:19]
	s_setprio 0
	s_barrier
; #define PG8_STAGE(bufoff, gbase, voff) do { _Pragma("unroll") for (int _i = 0; _i < 2; ++_i) glds16_s((gbase), (voff)[_i], ldsb + (unsigned)((bufoff) + _i * 8192)); } while (0)
; #define PG8_LDA(dst, b, h) do { _Pragma("unroll") for (int m = 0; m < 4; ++m) _Pragma("unroll") for (int k = 0; k < 2; ++k) dst[m][k] = *(const LAS h16x8*)(lds + PG8_SA(b, h) + aoff + m * 2048 + k * 1024); } while (0)
; #define PG8_LDB(dst, b, h) do { _Pragma("unroll") for (int n = 0; n < 2; ++n) _Pragma("unroll") for (int k = 0; k < 2; ++k) dst[n][k] = *(const LAS h16x8*)(lds + PG8_SB(b, h) + boff + n * 2048 + k * 1024); } while (0)
; #define PG8_WAIT_V(n) asm volatile("s_waitcnt vmcnt(" #n ")" ::: "memory")
; template <class Prob, class Epi, bool I8 = false, bool ALIGN_EPI = true, bool SP2 = true>
; __device__ __forceinline__ void gemm_phase(LAS unsigned char* lds, int wave, const Prob& P, const Epi& E) {
;     ...
;             PG8_LDB(B0, 1, 0); PG8_LDB(B1, 1, 1); PG8_SCHED; PG8_LDA(At, 1, 0); PG8_STAGE(PG8_SA(0, 1), a2 + hstepA, voffA);
;             PG8_WAIT_V(8); PG8_WAIT_L(0); PG8_BAR; PG8_MMA(0, 0, At, B0); PG8_MMA(0, 1, At, B1); PG8_BAR; PG8_SCHED;
;             PG8_LDA(At, 1, 1); PG8_STAGE(PG8_SB(1, 0), b3, voffB); PG8_STAGE(PG8_SB(1, 1), b3 + hstepB, voffB); PG8_STAGE(PG8_SA(1, 0), a3, voffA);
;             PG8_WAIT_V(8); PG8_WAIT_L(0); PG8_BAR; PG8_MMA(1, 0, At, B0); PG8_MMA(1, 1, At, B1); PG8_BAR; PG8_SCHED;
;     __device__ __forceinline__ void operator()(Acc& acc, const Unit& u, int wr, int wc, int fr, int fq, LAS unsigned char* lds, int tid) const {
;     ...
;         for (int bj = 0; bj < 2; ++bj) {
;             const unsigned colp = u.pn * 256 + bj * 128 + wc * 32 + 8 * fq;
;             const unsigned coll = bj * FF + u.pn * 128 + wc * 32 + 8 * fq;
; #pragma unroll
;             for (int n = 0; n < 2; ++n) {
;                 f32x4 c0 = ldf4(cw, coll + 4u * n), c1 = ldf4(cw, (unsigned)FF2 + coll + 4u * n), c2 = ldf4(cw, 2u * FF2 + coll + 4u * n);
;                 if constexpr (I8) { const f32x4 swv = ldf4(sw, colp + 4u * n); c0 = c0 * swv; c1 = c1 * swv; c2 = c2 * swv; }
;                 f32x4 hl = {0.f, 0.f, 0.f, 0.f}, hr = {0.f, 0.f, 0.f, 0.f};
;                 if (fr == 0 && lvalid) hl = ldf4(HALO, (2u * bk) * (unsigned)FF2 + colp + 4u * n);
;                 if (fr == 15 && rvalid) hr = ldf4(HALO, (2u * bk + 1u) * (unsigned)FF2 + colp + 4u * n);
	ds_read_b128 v[168:171], v211 offset:49152
	ds_read_b128 v[172:175], v211 offset:50176
	ds_read_b128 v[176:179], v211 offset:51200
	ds_read_b128 v[180:183], v211 offset:52224
	ds_read_b128 v[184:187], v211 offset:53248
	ds_read_b128 v[188:191], v211 offset:54272
	ds_read_b128 v[192:195], v211 offset:55296
	ds_read_b128 v[196:199], v211 offset:56320
	s_add_u32 s6, s68, 0x80
	s_addc_u32 s7, s69, 0
	s_mov_b32 s5, m0
	s_mov_b32 m0, s2
	s_nop 0
	global_load_lds_dwordx4 v217, s[6:7]
	s_mov_b32 m0, s5
	s_nop 0
	s_mov_b32 s5, m0
	s_mov_b32 m0, s85
	s_nop 0
	global_load_lds_dwordx4 v248, s[6:7]
	s_mov_b32 m0, s5
	s_add_u32 s6, s68, 0x40080
	s_addc_u32 s7, s69, 0
	s_mov_b32 s5, m0
	s_mov_b32 m0, s88
	s_nop 0
	global_load_lds_dwordx4 v217, s[6:7]
	s_mov_b32 m0, s5
	s_nop 0
	s_mov_b32 s5, m0
	s_mov_b32 m0, s89
	s_nop 0
	global_load_lds_dwordx4 v248, s[6:7]
	s_mov_b32 m0, s5
	s_nop 0
	s_mov_b32 s5, m0
	s_mov_b32 m0, s86
	s_nop 0
	global_load_lds_dwordx4 v250, s[60:61]
	s_mov_b32 m0, s5
	s_nop 0
	s_mov_b32 s5, m0
	s_mov_b32 m0, s87
	s_nop 0
	global_load_lds_dwordx4 v247, s[60:61]
	s_mov_b32 m0, s5
	s_waitcnt vmcnt(8)
	s_waitcnt lgkmcnt(0)
	s_barrier
	s_setprio 1
	s_waitcnt lgkmcnt(1)
	v_mfma_i32_16x16x64_i8 v[104:107], v[120:123], v[192:195], v[104:107]
	v_mfma_i32_16x16x64_i8 v[40:43], v[120:123], v[168:171], v[40:43]
	v_mfma_i32_16x16x64_i8 v[64:67], v[128:131], v[168:171], v[64:67]
	v_mfma_i32_16x16x64_i8 v[36:39], v[120:123], v[176:179], v[36:39]
	v_mfma_i32_16x16x64_i8 v[60:63], v[128:131], v[176:179], v[60:63]
	v_mfma_i32_16x16x64_i8 v[32:35], v[120:123], v[184:187], v[32:35]
	v_mfma_i32_16x16x64_i8 v[56:59], v[128:131], v[184:187], v[56:59]
	s_waitcnt lgkmcnt(0)
	v_mfma_i32_16x16x64_i8 v[156:159], v[124:127], v[196:199], v[104:107]
	v_mfma_i32_16x16x64_i8 v[104:107], v[128:131], v[192:195], v[112:115]
	v_mfma_i32_16x16x64_i8 v[40:43], v[124:127], v[172:175], v[40:43]
	v_mfma_i32_16x16x64_i8 v[64:67], v[132:135], v[172:175], v[64:67]
	v_mfma_i32_16x16x64_i8 v[36:39], v[124:127], v[180:183], v[36:39]
	v_mfma_i32_16x16x64_i8 v[60:63], v[132:135], v[180:183], v[60:63]
	v_mfma_i32_16x16x64_i8 v[32:35], v[124:127], v[188:191], v[32:35]
	v_mfma_i32_16x16x64_i8 v[56:59], v[132:135], v[188:191], v[56:59]
	v_mfma_i32_16x16x64_i8 v[148:151], v[132:135], v[196:199], v[104:107]
	s_setprio 0
	s_setprio 1
	v_mfma_i32_16x16x64_i8 v[88:91], v[136:139], v[168:171], v[88:91]
	v_mfma_i32_16x16x64_i8 v[12:15], v[144:147], v[168:171], v[12:15]
	v_mfma_i32_16x16x64_i8 v[84:87], v[136:139], v[176:179], v[84:87]
	v_mfma_i32_16x16x64_i8 v[8:11], v[144:147], v[176:179], v[8:11]
	v_mfma_i32_16x16x64_i8 v[76:79], v[136:139], v[184:187], v[76:79]
	v_mfma_i32_16x16x64_i8 v[4:7], v[144:147], v[184:187], v[4:7]
	v_mfma_i32_16x16x64_i8 v[104:107], v[136:139], v[192:195], v[108:111]
	v_mfma_i32_16x16x64_i8 v[0:3], v[144:147], v[192:195], v[0:3]
	v_mfma_i32_16x16x64_i8 v[88:91], v[140:143], v[172:175], v[88:91]
	v_mfma_i32_16x16x64_i8 v[12:15], v[164:167], v[172:175], v[12:15]
	v_mfma_i32_16x16x64_i8 v[84:87], v[140:143], v[180:183], v[84:87]
	v_mfma_i32_16x16x64_i8 v[8:11], v[164:167], v[180:183], v[8:11]
	v_mfma_i32_16x16x64_i8 v[76:79], v[140:143], v[188:191], v[76:79]
	v_mfma_i32_16x16x64_i8 v[4:7], v[164:167], v[188:191], v[4:7]
	v_mfma_i32_16x16x64_i8 v[108:111], v[140:143], v[196:199], v[104:107]
	v_mfma_i32_16x16x64_i8 v[0:3], v[164:167], v[196:199], v[0:3]
	s_setprio 0
	s_barrier
	s_add_i32 s4, s4, 2
	s_add_u32 vcc_lo, vcc_lo, 0x100
	s_addc_u32 vcc_hi, vcc_hi, 0
	s_add_u32 s0, s0, 0x100
	s_addc_u32 s1, s1, 0
	s_add_u32 s44, s44, 0x100
	s_addc_u32 s45, s45, 0
	s_cmp_gt_u32 s4, 11
	s_cbranch_scc0 .LBB0_1065
.Llast_1065:
	v_mbcnt_lo_u32_b32 v200, -1, 0
	v_mbcnt_hi_u32_b32 v200, -1, v200
	s_lshl_b32 s101, s94, 8
	s_or_b32 s101, s101, s84
	v_lshrrev_b32_e32 v200, 1, v200
	v_and_b32_e32 v200, 24, v200
	v_or_b32_e32 v200, s101, v200
	s_lshl_b32 s100, s95, 1
	s_add_i32 s100, s100, s64
	s_mulk_i32 s100, 0x5800
	s_add_i32 s101, s100, 0x2c00
	v_add_u32_e32 v201, s100, v200
	v_add_u32_e32 v202, s101, v200
	v_lshlrev_b32_e32 v201, 2, v201
	v_lshlrev_b32_e32 v202, 2, v202
	global_load_dwordx4 v[220:223], v201, s[38:39]
	global_load_dwordx4 v[224:227], v202, s[38:39]
	global_load_dwordx4 v[228:231], v201, s[38:39] offset:512
	global_load_dwordx4 v[232:235], v202, s[38:39] offset:512
	v_add_u32_e32 v124, 0x10000, v210
	v_add_u32_e32 v140, 0x14000, v210
	ds_read_b128 v[104:107], v124
	ds_read_b128 v[112:115], v124 offset:1024
	ds_read_b128 v[120:123], v124 offset:2048
	ds_read_b128 v[124:127], v124 offset:3072
	ds_read_b128 v[128:131], v140
	ds_read_b128 v[132:135], v140 offset:1024
	ds_read_b128 v[136:139], v140 offset:2048
	ds_read_b128 v[140:143], v140 offset:3072
	s_cmp_eq_u32 s4, 12
	s_cselect_b32 s62, s96, vcc_lo
	s_cselect_b32 s63, s51, vcc_hi
	s_cselect_b32 s68, s97, s0
	s_cselect_b32 s69, s49, s1
	s_add_u32 s60, s62, 0x80
	s_addc_u32 s61, s63, 0
	ds_read_b128 v[144:147], v211
	ds_read_b128 v[164:167], v211 offset:1024
	ds_read_b128 v[168:171], v211 offset:2048
	ds_read_b128 v[172:175], v211 offset:3072
	ds_read_b128 v[176:179], v211 offset:4096
	ds_read_b128 v[180:183], v211 offset:5120
	ds_read_b128 v[184:187], v211 offset:6144
	ds_read_b128 v[188:191], v211 offset:7168
	s_mov_b32 s5, m0
	s_mov_b32 m0, s90
	s_nop 0
	global_load_lds_dwordx4 v250, s[44:45]
	s_mov_b32 m0, s5
	s_nop 0
	s_mov_b32 s5, m0
	s_mov_b32 m0, s92
	s_nop 0
	global_load_lds_dwordx4 v247, s[44:45]
	s_mov_b32 m0, s5
	s_waitcnt vmcnt(12)
	s_waitcnt lgkmcnt(0)
	s_barrier
; #define PG8_STAGE(bufoff, gbase, voff) do { _Pragma("unroll") for (int _i = 0; _i < 2; ++_i) glds16_s((gbase), (voff)[_i], ldsb + (unsigned)((bufoff) + _i * 8192)); } while (0)
; #define PG8_LDA(dst, b, h) do { _Pragma("unroll") for (int m = 0; m < 4; ++m) _Pragma("unroll") for (int k = 0; k < 2; ++k) dst[m][k] = *(const LAS h16x8*)(lds + PG8_SA(b, h) + aoff + m * 2048 + k * 1024); } while (0)
; #define PG8_LDB(dst, b, h) do { _Pragma("unroll") for (int n = 0; n < 2; ++n) _Pragma("unroll") for (int k = 0; k < 2; ++k) dst[n][k] = *(const LAS h16x8*)(lds + PG8_SB(b, h) + boff + n * 2048 + k * 1024); } while (0)
; #define PG8_MMA(ai, bj, At, Bt) do { __builtin_amdgcn_s_setprio(1); _Pragma("unroll") for (int m = 0; m < 4; ++m) _Pragma("unroll") for (int n = 0; n < 2; ++n) _Pragma("unroll") for (int k = 0; k < 2; ++k) \
;         acc[ai][bj][m][n] = mma_step<I8>(Bt[n][k], At[m][k], acc[ai][bj][m][n]); __builtin_amdgcn_s_setprio(0); } while (0)
; #define PG8_WAIT_V(n) asm volatile("s_waitcnt vmcnt(" #n ")" ::: "memory")
; #define PG8_WAIT_L(n) asm volatile("s_waitcnt lgkmcnt(" #n ")" ::: "memory")
; #define PG8_BAR __builtin_amdgcn_s_barrier()
; #define PG8_SCHED __builtin_amdgcn_sched_barrier(0)
; template <class Prob, class Epi, bool I8 = false, bool ALIGN_EPI = true, bool SP2 = true>
; __device__ __forceinline__ void gemm_phase(LAS unsigned char* lds, int wave, const Prob& P, const Epi& E) {
;     ...
;             PG8_LDB(B0, 0, 0); PG8_LDB(B1, 0, 1); PG8_SCHED; PG8_LDA(At, 0, 0); PG8_STAGE(PG8_SA(1, 1), a1 + hstepA, voffA);
;             PG8_WAIT_V(8); PG8_WAIT_L(0); PG8_BAR; PG8_MMA(0, 0, At, B0); PG8_MMA(0, 1, At, B1); PG8_BAR; PG8_SCHED;
;             PG8_LDA(At, 0, 1); PG8_STAGE(PG8_SB(0, 0), b2, voffB); PG8_STAGE(PG8_SB(0, 1), b2 + hstepB, voffB); PG8_STAGE(PG8_SA(0, 0), a2, voffA);
;             PG8_WAIT_V(8); PG8_WAIT_L(0); PG8_BAR; PG8_MMA(1, 0, At, B0); PG8_MMA(1, 1, At, B1); PG8_BAR; PG8_SCHED;
	s_setprio 1
	s_waitcnt lgkmcnt(7)
	v_mfma_i32_16x16x64_i8 v[160:163], v[104:107], v[144:147], v[160:163]
	v_mfma_i32_16x16x64_i8 v[152:155], v[120:123], v[144:147], v[152:155]
	s_waitcnt lgkmcnt(5)
	v_mfma_i32_16x16x64_i8 v[52:55], v[104:107], v[168:171], v[52:55]
	v_mfma_i32_16x16x64_i8 v[80:83], v[120:123], v[168:171], v[80:83]
	s_waitcnt lgkmcnt(3)
	v_mfma_i32_16x16x64_i8 v[48:51], v[104:107], v[176:179], v[48:51]
	v_mfma_i32_16x16x64_i8 v[72:75], v[120:123], v[176:179], v[72:75]
	s_waitcnt lgkmcnt(1)
	v_mfma_i32_16x16x64_i8 v[44:47], v[104:107], v[184:187], v[44:47]
	v_mfma_i32_16x16x64_i8 v[68:71], v[120:123], v[184:187], v[68:71]
	v_mfma_i32_16x16x64_i8 v[160:163], v[112:115], v[164:167], v[160:163]
	v_mfma_i32_16x16x64_i8 v[152:155], v[124:127], v[164:167], v[152:155]
	v_mfma_i32_16x16x64_i8 v[52:55], v[112:115], v[172:175], v[52:55]
	v_mfma_i32_16x16x64_i8 v[80:83], v[124:127], v[172:175], v[80:83]
	v_mfma_i32_16x16x64_i8 v[48:51], v[112:115], v[180:183], v[48:51]
	v_mfma_i32_16x16x64_i8 v[72:75], v[124:127], v[180:183], v[72:75]
	s_waitcnt lgkmcnt(0)
	v_mfma_i32_16x16x64_i8 v[44:47], v[112:115], v[188:191], v[44:47]
	v_mfma_i32_16x16x64_i8 v[68:71], v[124:127], v[188:191], v[68:71]
	s_setprio 0
	s_setprio 1
	v_mfma_i32_16x16x64_i8 v[116:119], v[128:131], v[144:147], v[116:119]
	v_mfma_i32_16x16x64_i8 v[28:31], v[136:139], v[144:147], v[28:31]
	v_mfma_i32_16x16x64_i8 v[100:103], v[128:131], v[168:171], v[100:103]
	v_mfma_i32_16x16x64_i8 v[24:27], v[136:139], v[168:171], v[24:27]
	v_mfma_i32_16x16x64_i8 v[96:99], v[128:131], v[176:179], v[96:99]
	v_mfma_i32_16x16x64_i8 v[20:23], v[136:139], v[176:179], v[20:23]
	v_mfma_i32_16x16x64_i8 v[92:95], v[128:131], v[184:187], v[92:95]
	v_mfma_i32_16x16x64_i8 v[16:19], v[136:139], v[184:187], v[16:19]
	v_mfma_i32_16x16x64_i8 v[116:119], v[132:135], v[164:167], v[116:119]
	v_mfma_i32_16x16x64_i8 v[28:31], v[140:143], v[164:167], v[28:31]
	v_mfma_i32_16x16x64_i8 v[100:103], v[132:135], v[172:175], v[100:103]
	v_mfma_i32_16x16x64_i8 v[24:27], v[140:143], v[172:175], v[24:27]
	v_mfma_i32_16x16x64_i8 v[96:99], v[132:135], v[180:183], v[96:99]
	v_mfma_i32_16x16x64_i8 v[20:23], v[140:143], v[180:183], v[20:23]
	v_mfma_i32_16x16x64_i8 v[92:95], v[132:135], v[188:191], v[92:95]
	v_mfma_i32_16x16x64_i8 v[16:19], v[140:143], v[188:191], v[16:19]
	s_setprio 0
	s_barrier
	ds_read_b128 v[144:147], v211 offset:16384
	ds_read_b128 v[164:167], v211 offset:17408
	ds_read_b128 v[168:171], v211 offset:18432
	ds_read_b128 v[172:175], v211 offset:19456
	ds_read_b128 v[176:179], v211 offset:20480
	ds_read_b128 v[180:183], v211 offset:21504
	ds_read_b128 v[184:187], v211 offset:22528
	ds_read_b128 v[188:191], v211 offset:23552
	s_mov_b32 s5, m0
	s_mov_b32 m0, s73
	s_nop 0
	global_load_lds_dwordx4 v217, s[68:69]
	s_mov_b32 m0, s5
	s_add_u32 s6, s68, 0x40000
	s_mov_b32 s5, m0
	s_mov_b32 m0, s74
	s_nop 0
	global_load_lds_dwordx4 v248, s[68:69]
	s_mov_b32 m0, s5
	s_addc_u32 s7, s69, 0
	s_mov_b32 s5, m0
	s_mov_b32 m0, s75
	s_nop 0
	global_load_lds_dwordx4 v217, s[6:7]
	s_mov_b32 m0, s5
	s_nop 0
	s_mov_b32 s5, m0
	s_mov_b32 m0, s80
	s_nop 0
	global_load_lds_dwordx4 v248, s[6:7]
	s_mov_b32 m0, s5
	s_nop 0
	s_mov_b32 s5, m0
	s_mov_b32 m0, s72
	s_nop 0
	global_load_lds_dwordx4 v250, s[62:63]
	s_mov_b32 m0, s5
	s_nop 0
	s_mov_b32 s5, m0
	s_mov_b32 m0, s81
	s_nop 0
	global_load_lds_dwordx4 v247, s[62:63]
	s_mov_b32 m0, s5
	s_waitcnt vmcnt(12)
	s_waitcnt lgkmcnt(0)
	s_barrier
	s_setprio 1
	s_waitcnt lgkmcnt(7)
	v_mfma_i32_16x16x64_i8 v[40:43], v[104:107], v[144:147], v[40:43]
	v_mfma_i32_16x16x64_i8 v[64:67], v[120:123], v[144:147], v[64:67]
	s_waitcnt lgkmcnt(5)
	v_mfma_i32_16x16x64_i8 v[36:39], v[104:107], v[168:171], v[36:39]
	v_mfma_i32_16x16x64_i8 v[60:63], v[120:123], v[168:171], v[60:63]
	s_waitcnt lgkmcnt(3)
	v_mfma_i32_16x16x64_i8 v[32:35], v[104:107], v[176:179], v[32:35]
	v_mfma_i32_16x16x64_i8 v[56:59], v[120:123], v[176:179], v[56:59]
	s_waitcnt lgkmcnt(1)
	v_mfma_i32_16x16x64_i8 v[104:107], v[104:107], v[184:187], v[156:159]
	v_mfma_i32_16x16x64_i8 v[40:43], v[112:115], v[164:167], v[40:43]
	v_mfma_i32_16x16x64_i8 v[64:67], v[124:127], v[164:167], v[64:67]
	v_mfma_i32_16x16x64_i8 v[36:39], v[112:115], v[172:175], v[36:39]
	v_mfma_i32_16x16x64_i8 v[60:63], v[124:127], v[172:175], v[60:63]
	v_mfma_i32_16x16x64_i8 v[32:35], v[112:115], v[180:183], v[32:35]
	v_mfma_i32_16x16x64_i8 v[56:59], v[124:127], v[180:183], v[56:59]
	s_waitcnt lgkmcnt(0)
	v_mfma_i32_16x16x64_i8 v[104:107], v[112:115], v[188:191], v[104:107]
	v_mfma_i32_16x16x64_i8 v[112:115], v[120:123], v[184:187], v[148:151]
	v_mfma_i32_16x16x64_i8 v[112:115], v[124:127], v[188:191], v[112:115]
	s_setprio 0
	s_setprio 1
	v_mfma_i32_16x16x64_i8 v[88:91], v[128:131], v[144:147], v[88:91]
	v_mfma_i32_16x16x64_i8 v[12:15], v[136:139], v[144:147], v[12:15]
	v_mfma_i32_16x16x64_i8 v[84:87], v[128:131], v[168:171], v[84:87]
	v_mfma_i32_16x16x64_i8 v[8:11], v[136:139], v[168:171], v[8:11]
	v_mfma_i32_16x16x64_i8 v[76:79], v[128:131], v[176:179], v[76:79]
	v_mfma_i32_16x16x64_i8 v[4:7], v[136:139], v[176:179], v[4:7]
	v_mfma_i32_16x16x64_i8 v[108:111], v[128:131], v[184:187], v[108:111]
	v_mfma_i32_16x16x64_i8 v[0:3], v[136:139], v[184:187], v[0:3]
	v_mfma_i32_16x16x64_i8 v[88:91], v[132:135], v[164:167], v[88:91]
	v_mfma_i32_16x16x64_i8 v[12:15], v[140:143], v[164:167], v[12:15]
	v_mfma_i32_16x16x64_i8 v[84:87], v[132:135], v[172:175], v[84:87]
	v_mfma_i32_16x16x64_i8 v[8:11], v[140:143], v[172:175], v[8:11]
	v_mfma_i32_16x16x64_i8 v[76:79], v[132:135], v[180:183], v[76:79]
	v_mfma_i32_16x16x64_i8 v[4:7], v[140:143], v[180:183], v[4:7]
	v_mfma_i32_16x16x64_i8 v[108:111], v[132:135], v[188:191], v[108:111]
	v_mfma_i32_16x16x64_i8 v[0:3], v[140:143], v[188:191], v[0:3]
	s_setprio 0
	s_barrier
; #define PG8_STAGE(bufoff, gbase, voff) do { _Pragma("unroll") for (int _i = 0; _i < 2; ++_i) glds16_s((gbase), (voff)[_i], ldsb + (unsigned)((bufoff) + _i * 8192)); } while (0)
; #define PG8_LDA(dst, b, h) do { _Pragma("unroll") for (int m = 0; m < 4; ++m) _Pragma("unroll") for (int k = 0; k < 2; ++k) dst[m][k] = *(const LAS h16x8*)(lds + PG8_SA(b, h) + aoff + m * 2048 + k * 1024); } while (0)
; #define PG8_LDB(dst, b, h) do { _Pragma("unroll") for (int n = 0; n < 2; ++n) _Pragma("unroll") for (int k = 0; k < 2; ++k) dst[n][k] = *(const LAS h16x8*)(lds + PG8_SB(b, h) + boff + n * 2048 + k * 1024); } while (0)
; #define PG8_MMA(ai, bj, At, Bt) do { __builtin_amdgcn_s_setprio(1); _Pragma("unroll") for (int m = 0; m < 4; ++m) _Pragma("unroll") for (int n = 0; n < 2; ++n) _Pragma("unroll") for (int k = 0; k < 2; ++k) \
;         acc[ai][bj][m][n] = mma_step<I8>(Bt[n][k], At[m][k], acc[ai][bj][m][n]); __builtin_amdgcn_s_setprio(0); } while (0)
; #define PG8_WAIT_V(n) asm volatile("s_waitcnt vmcnt(" #n ")" ::: "memory")
; #define PG8_WAIT_L(n) asm volatile("s_waitcnt lgkmcnt(" #n ")" ::: "memory")
; #define PG8_BAR __builtin_amdgcn_s_barrier()
; #define PG8_SCHED __builtin_amdgcn_sched_barrier(0)
; template <class Prob, class Epi, bool I8 = false, bool ALIGN_EPI = true, bool SP2 = true>
; __device__ __forceinline__ void gemm_phase(LAS unsigned char* lds, int wave, const Prob& P, const Epi& E) {
;     ...
;             PG8_WAIT_V(8); PG8_WAIT_L(0); PG8_BAR; PG8_MMA(1, 0, At, B0); PG8_MMA(1, 1, At, B1); PG8_BAR; PG8_SCHED;
;             PG8_LDB(B0, 1, 0); PG8_LDB(B1, 1, 1); PG8_SCHED; PG8_LDA(At, 1, 0); PG8_STAGE(PG8_SA(0, 1), a2 + hstepA, voffA);
;             PG8_WAIT_V(8); PG8_WAIT_L(0); PG8_BAR; PG8_MMA(0, 0, At, B0); PG8_MMA(0, 1, At, B1); PG8_BAR; PG8_SCHED;
;             PG8_LDA(At, 1, 1); PG8_STAGE(PG8_SB(1, 0), b3, voffB); PG8_STAGE(PG8_SB(1, 1), b3 + hstepB, voffB); PG8_STAGE(PG8_SA(1, 0), a3, voffA);
	v_add_u32_e32 v132, 0x18000, v210
	v_add_u32_e32 v148, 0x1c000, v210
	ds_read_b128 v[120:123], v132
	ds_read_b128 v[124:127], v132 offset:1024
	ds_read_b128 v[128:131], v132 offset:2048
	ds_read_b128 v[132:135], v132 offset:3072
	ds_read_b128 v[136:139], v148
	ds_read_b128 v[140:143], v148 offset:1024
	ds_read_b128 v[144:147], v148 offset:2048
	ds_read_b128 v[164:167], v148 offset:3072
	ds_read_b128 v[148:151], v211 offset:32768
	ds_read_b128 v[156:159], v211 offset:33792
	ds_read_b128 v[168:171], v211 offset:34816
	ds_read_b128 v[172:175], v211 offset:35840
	ds_read_b128 v[176:179], v211 offset:36864
	ds_read_b128 v[180:183], v211 offset:37888
	ds_read_b128 v[184:187], v211 offset:38912
	ds_read_b128 v[188:191], v211 offset:39936
	s_add_u32 s6, s62, 0x2000
	s_addc_u32 s7, s63, 0
	s_mov_b32 s5, m0
	s_mov_b32 m0, s82
	s_nop 0
	global_load_lds_dwordx4 v250, s[6:7]
	s_mov_b32 m0, s5
	s_nop 0
	s_mov_b32 s5, m0
	s_mov_b32 m0, s83
	s_nop 0
	global_load_lds_dwordx4 v247, s[6:7]
	s_mov_b32 m0, s5
	s_waitcnt vmcnt(8)
	s_waitcnt lgkmcnt(0)
	s_barrier
	s_setprio 1
	s_waitcnt lgkmcnt(7)
	v_mfma_i32_16x16x64_i8 v[160:163], v[120:123], v[148:151], v[160:163]
	v_mfma_i32_16x16x64_i8 v[152:155], v[128:131], v[148:151], v[152:155]
	s_waitcnt lgkmcnt(5)
	v_mfma_i32_16x16x64_i8 v[52:55], v[120:123], v[168:171], v[52:55]
	v_mfma_i32_16x16x64_i8 v[80:83], v[128:131], v[168:171], v[80:83]
	s_waitcnt lgkmcnt(3)
	v_mfma_i32_16x16x64_i8 v[48:51], v[120:123], v[176:179], v[48:51]
	v_mfma_i32_16x16x64_i8 v[72:75], v[128:131], v[176:179], v[72:75]
	s_waitcnt lgkmcnt(1)
	v_mfma_i32_16x16x64_i8 v[44:47], v[120:123], v[184:187], v[44:47]
	v_mfma_i32_16x16x64_i8 v[68:71], v[128:131], v[184:187], v[68:71]
	v_mfma_i32_16x16x64_i8 v[160:163], v[124:127], v[156:159], v[160:163]
	v_mfma_i32_16x16x64_i8 v[152:155], v[132:135], v[156:159], v[152:155]
	v_mfma_i32_16x16x64_i8 v[52:55], v[124:127], v[172:175], v[52:55]
	v_mfma_i32_16x16x64_i8 v[80:83], v[132:135], v[172:175], v[80:83]
	v_mfma_i32_16x16x64_i8 v[48:51], v[124:127], v[180:183], v[48:51]
	v_mfma_i32_16x16x64_i8 v[72:75], v[132:135], v[180:183], v[72:75]
	s_waitcnt lgkmcnt(0)
	v_mfma_i32_16x16x64_i8 v[44:47], v[124:127], v[188:191], v[44:47]
	v_mfma_i32_16x16x64_i8 v[68:71], v[132:135], v[188:191], v[68:71]
	s_setprio 0
	s_setprio 1
	v_mfma_i32_16x16x64_i8 v[116:119], v[136:139], v[148:151], v[116:119]
	v_mfma_i32_16x16x64_i8 v[28:31], v[144:147], v[148:151], v[28:31]
	v_mfma_i32_16x16x64_i8 v[100:103], v[136:139], v[168:171], v[100:103]
	v_mfma_i32_16x16x64_i8 v[24:27], v[144:147], v[168:171], v[24:27]
	v_mfma_i32_16x16x64_i8 v[96:99], v[136:139], v[176:179], v[96:99]
	v_mfma_i32_16x16x64_i8 v[20:23], v[144:147], v[176:179], v[20:23]
	v_mfma_i32_16x16x64_i8 v[92:95], v[136:139], v[184:187], v[92:95]
	v_mfma_i32_16x16x64_i8 v[16:19], v[144:147], v[184:187], v[16:19]
	v_mfma_i32_16x16x64_i8 v[116:119], v[140:143], v[156:159], v[116:119]
	v_mfma_i32_16x16x64_i8 v[28:31], v[164:167], v[156:159], v[28:31]
	v_mfma_i32_16x16x64_i8 v[100:103], v[140:143], v[172:175], v[100:103]
	v_mfma_i32_16x16x64_i8 v[24:27], v[164:167], v[172:175], v[24:27]
	v_mfma_i32_16x16x64_i8 v[96:99], v[140:143], v[180:183], v[96:99]
	v_mfma_i32_16x16x64_i8 v[20:23], v[164:167], v[180:183], v[20:23]
	v_mfma_i32_16x16x64_i8 v[92:95], v[140:143], v[188:191], v[92:95]
	v_mfma_i32_16x16x64_i8 v[16:19], v[164:167], v[188:191], v[16:19]
	s_setprio 0
	s_barrier
	ds_read_b128 v[168:171], v211 offset:49152
	ds_read_b128 v[172:175], v211 offset:50176
	ds_read_b128 v[176:179], v211 offset:51200
	ds_read_b128 v[180:183], v211 offset:52224
	ds_read_b128 v[184:187], v211 offset:53248
	ds_read_b128 v[188:191], v211 offset:54272
	ds_read_b128 v[192:195], v211 offset:55296
	ds_read_b128 v[196:199], v211 offset:56320
	s_add_u32 s6, s68, 0x80
	s_addc_u32 s7, s69, 0
	s_mov_b32 s5, m0
	s_mov_b32 m0, s2
	s_nop 0
	global_load_lds_dwordx4 v217, s[6:7]
	s_mov_b32 m0, s5
	s_nop 0
	s_mov_b32 s5, m0
	s_mov_b32 m0, s85
	s_nop 0
	global_load_lds_dwordx4 v248, s[6:7]
	s_mov_b32 m0, s5
	s_add_u32 s6, s68, 0x40080
	s_addc_u32 s7, s69, 0
	s_mov_b32 s5, m0
	s_mov_b32 m0, s88
	s_nop 0
	global_load_lds_dwordx4 v217, s[6:7]
	s_mov_b32 m0, s5
	s_nop 0
	s_mov_b32 s5, m0
	s_mov_b32 m0, s89
	s_nop 0
	global_load_lds_dwordx4 v248, s[6:7]
	s_mov_b32 m0, s5
	s_nop 0
	s_mov_b32 s5, m0
	s_mov_b32 m0, s86
	s_nop 0
	global_load_lds_dwordx4 v250, s[60:61]
	s_mov_b32 m0, s5
	s_nop 0
	s_mov_b32 s5, m0
	s_mov_b32 m0, s87
	s_nop 0
	global_load_lds_dwordx4 v247, s[60:61]
	s_mov_b32 m0, s5
	s_waitcnt vmcnt(8)
	s_waitcnt lgkmcnt(0)
	s_barrier
; #define PG8_STAGE(bufoff, gbase, voff) do { _Pragma("unroll") for (int _i = 0; _i < 2; ++_i) glds16_s((gbase), (voff)[_i], ldsb + (unsigned)((bufoff) + _i * 8192)); } while (0)
; #define PG8_LDA(dst, b, h) do { _Pragma("unroll") for (int m = 0; m < 4; ++m) _Pragma("unroll") for (int k = 0; k < 2; ++k) dst[m][k] = *(const LAS h16x8*)(lds + PG8_SA(b, h) + aoff + m * 2048 + k * 1024); } while (0)
; #define PG8_MMA(ai, bj, At, Bt) do { __builtin_amdgcn_s_setprio(1); _Pragma("unroll") for (int m = 0; m < 4; ++m) _Pragma("unroll") for (int n = 0; n < 2; ++n) _Pragma("unroll") for (int k = 0; k < 2; ++k) \
;         acc[ai][bj][m][n] = mma_step<I8>(Bt[n][k], At[m][k], acc[ai][bj][m][n]); __builtin_amdgcn_s_setprio(0); } while (0)
; #define PG8_WAIT_V(n) asm volatile("s_waitcnt vmcnt(" #n ")" ::: "memory")
; template <class Prob, class Epi, bool I8 = false, bool ALIGN_EPI = true, bool SP2 = true>
; __device__ __forceinline__ void gemm_phase(LAS unsigned char* lds, int wave, const Prob& P, const Epi& E) {
;     ...
;             PG8_LDA(At, 1, 1); PG8_STAGE(PG8_SB(1, 0), b3, voffB); PG8_STAGE(PG8_SB(1, 1), b3 + hstepB, voffB); PG8_STAGE(PG8_SA(1, 0), a3, voffA);
;             PG8_WAIT_V(8); PG8_WAIT_L(0); PG8_BAR; PG8_MMA(1, 0, At, B0); PG8_MMA(1, 1, At, B1); PG8_BAR; PG8_SCHED;
;     __device__ __forceinline__ void operator()(Acc& acc, const Unit& u, int wr, int wc, int fr, int fq, LAS unsigned char* lds, int tid) const {
;     ...
;         const unsigned bk = 2 * u.pm + wr;
;         const bool lvalid = (bk & 15) != 0, rvalid = (bk & 15) != 15;
; #pragma unroll
;         for (int bj = 0; bj < 2; ++bj) {
;             const unsigned colp = u.pn * 256 + bj * 128 + wc * 32 + 8 * fq;
;             const unsigned coll = bj * FF + u.pn * 128 + wc * 32 + 8 * fq;
; #pragma unroll
;             for (int n = 0; n < 2; ++n) {
;                 f32x4 c0 = ldf4(cw, coll + 4u * n), c1 = ldf4(cw, (unsigned)FF2 + coll + 4u * n), c2 = ldf4(cw, 2u * FF2 + coll + 4u * n);
;                 if constexpr (I8) { const f32x4 swv = ldf4(sw, colp + 4u * n); c0 = c0 * swv; c1 = c1 * swv; c2 = c2 * swv; }
;                 f32x4 hl = {0.f, 0.f, 0.f, 0.f}, hr = {0.f, 0.f, 0.f, 0.f};
;                 if (fr == 0 && lvalid) hl = ldf4(HALO, (2u * bk) * (unsigned)FF2 + colp + 4u * n);
;                 if (fr == 15 && rvalid) hr = ldf4(HALO, (2u * bk + 1u) * (unsigned)FF2 + colp + 4u * n);
	s_setprio 1
	s_waitcnt lgkmcnt(1)
	v_mfma_i32_16x16x64_i8 v[104:107], v[120:123], v[192:195], v[104:107]
	v_mfma_i32_16x16x64_i8 v[40:43], v[120:123], v[168:171], v[40:43]
	v_mfma_i32_16x16x64_i8 v[64:67], v[128:131], v[168:171], v[64:67]
	v_mfma_i32_16x16x64_i8 v[36:39], v[120:123], v[176:179], v[36:39]
	v_mfma_i32_16x16x64_i8 v[60:63], v[128:131], v[176:179], v[60:63]
	v_mfma_i32_16x16x64_i8 v[32:35], v[120:123], v[184:187], v[32:35]
	v_mfma_i32_16x16x64_i8 v[56:59], v[128:131], v[184:187], v[56:59]
	s_waitcnt lgkmcnt(0)
	v_mfma_i32_16x16x64_i8 v[156:159], v[124:127], v[196:199], v[104:107]
	v_mfma_i32_16x16x64_i8 v[104:107], v[128:131], v[192:195], v[112:115]
	v_mfma_i32_16x16x64_i8 v[40:43], v[124:127], v[172:175], v[40:43]
	v_mfma_i32_16x16x64_i8 v[64:67], v[132:135], v[172:175], v[64:67]
	v_mfma_i32_16x16x64_i8 v[36:39], v[124:127], v[180:183], v[36:39]
	v_mfma_i32_16x16x64_i8 v[60:63], v[132:135], v[180:183], v[60:63]
	v_mfma_i32_16x16x64_i8 v[32:35], v[124:127], v[188:191], v[32:35]
	v_mfma_i32_16x16x64_i8 v[56:59], v[132:135], v[188:191], v[56:59]
	v_mfma_i32_16x16x64_i8 v[148:151], v[132:135], v[196:199], v[104:107]
	s_setprio 0
	s_setprio 1
	v_mfma_i32_16x16x64_i8 v[88:91], v[136:139], v[168:171], v[88:91]
	v_mfma_i32_16x16x64_i8 v[12:15], v[144:147], v[168:171], v[12:15]
	v_mfma_i32_16x16x64_i8 v[84:87], v[136:139], v[176:179], v[84:87]
	v_mfma_i32_16x16x64_i8 v[8:11], v[144:147], v[176:179], v[8:11]
	v_mfma_i32_16x16x64_i8 v[76:79], v[136:139], v[184:187], v[76:79]
	v_mfma_i32_16x16x64_i8 v[4:7], v[144:147], v[184:187], v[4:7]
	v_mfma_i32_16x16x64_i8 v[104:107], v[136:139], v[192:195], v[108:111]
	v_mfma_i32_16x16x64_i8 v[0:3], v[144:147], v[192:195], v[0:3]
	v_mfma_i32_16x16x64_i8 v[88:91], v[140:143], v[172:175], v[88:91]
	v_mfma_i32_16x16x64_i8 v[12:15], v[164:167], v[172:175], v[12:15]
	v_mfma_i32_16x16x64_i8 v[84:87], v[140:143], v[180:183], v[84:87]
	v_mfma_i32_16x16x64_i8 v[8:11], v[164:167], v[180:183], v[8:11]
	v_mfma_i32_16x16x64_i8 v[76:79], v[140:143], v[188:191], v[76:79]
	v_mfma_i32_16x16x64_i8 v[4:7], v[164:167], v[188:191], v[4:7]
	v_mfma_i32_16x16x64_i8 v[108:111], v[140:143], v[196:199], v[104:107]
	v_mfma_i32_16x16x64_i8 v[0:3], v[164:167], v[196:199], v[0:3]
	s_setprio 0
	s_barrier
	s_add_i32 s4, s4, 2
	s_add_u32 vcc_lo, vcc_lo, 0x100
	s_addc_u32 vcc_hi, vcc_hi, 0
	s_add_u32 s0, s0, 0x100
	s_addc_u32 s1, s1, 0
	s_add_u32 s44, s44, 0x100
	s_addc_u32 s45, s45, 0
	s_mov_b32 s100, 0xbfb8aa3b
	s_mov_b32 s101, 0
	s_and_b64 vcc, exec, s[46:47]
	s_cbranch_vccz .LBB0_1068
	s_barrier
.LBB0_1068:
	s_lshl_b32 s0, s95, 8
	v_mbcnt_lo_u32_b32 v120, -1, 0
	v_mbcnt_hi_u32_b32 v120, -1, v120
	s_add_i32 s0, s0, s91
	v_and_b32_e32 v124, 15, v120
	v_lshl_or_b32 v212, v124, 3, s0
	s_lshl_b32 s0, s95, 1
	s_add_i32 s1, s0, s64
	s_and_b32 s0, s1, 15
	s_cmp_lg_u32 s0, 0
	s_cselect_b64 s[4:5], -1, 0
	s_lshl_b32 s6, s94, 8
	v_lshrrev_b32_e32 v120, 1, v120
	s_or_b32 s6, s6, s84
	v_and_b32_e32 v120, 24, v120
	v_or_b32_e32 v177, s6, v120
	s_lshl_b32 s6, s94, 7
	s_or_b32 s6, s6, s84
	v_lshlrev_b32_e32 v104, 2, v212
	v_or_b32_e32 v213, s6, v120
	global_load_dwordx4 v[112:115], v104, s[26:27]
	v_or_b32_e32 v104, 16, v104
	v_lshlrev_b32_e32 v208, 2, v213
	global_load_dwordx4 v[104:107], v104, s[26:27]
	v_add_u32_e32 v120, 0xb000, v208
	v_lshlrev_b32_e32 v146, 2, v177
	global_load_dwordx4 v[136:139], v208, s[22:23]
	v_add_u32_e32 v121, 0x16000, v208
	global_load_dwordx4 v[140:143], v120, s[22:23]
	global_load_dwordx4 v[128:131], v121, s[22:23]
	global_load_dwordx4 v[132:135], v146, s[28:29]
	v_cmp_eq_u32_e32 vcc, 0, v124
	s_mulk_i32 s1, 0x5800
	s_and_b64 s[44:45], vcc, s[4:5]
	v_add_u32_e32 v172, s1, v177
	s_waitcnt vmcnt(22)
	s_cmp_lg_u64 s[44:45], 0
	s_cbranch_scc1 .Lzs_0
	v_mov_b32_e32 v144, 0
	v_mov_b32_e32 v120, 0
	v_mov_b32_e32 v121, 0
	v_mov_b32_e32 v122, 0
	v_mov_b32_e32 v123, 0
.Lzs_0:
	s_and_saveexec_b64 s[60:61], s[44:45]
	v_mov_b32_e32 v120, v220
	v_mov_b32_e32 v121, v221
	v_mov_b32_e32 v122, v222
	v_mov_b32_e32 v123, v223

;     __device__ bool next(int i, Unit& u) const { return S.next(i, u); }
;     __device__ bool next(int i, Unit& u) const { const int L = i * G + c; if (L >= 3 * 44) return false; u.pm = L % 3; u.pn = L / 3; u.g = 0; u.part = 0; u.keep = 0; return true; }
;     __device__ __forceinline__ void operator()(Acc& acc, const Unit& u, int wr, int wc, int fr, int fq, LAS unsigned char* lds, int tid) const {
;     ...
;         if constexpr (I8) {
; #pragma unroll
;             for (int ai = 0; ai < 2; ++ai) { const f32x4 sa = ldf4(sx, tok0 + tl0 + 4u * ai);
; #pragma unroll
;                 for (int m = 0; m < 4; ++m)
; #pragma unroll
;                     for (int bj = 0; bj < 2; ++bj)
; #pragma unroll
;                         for (int n = 0; n < 2; ++n) { const pg8::i32x4 iv = __builtin_bit_cast(pg8::i32x4, acc[ai][bj][m][n]); acc[ai][bj][m][n] = __builtin_convertvector(iv, f32x4) * sa[m]; }
;                 asm volatile("" ::: "memory"); }
;         }
;         const unsigned bk = 2 * u.pm + wr;
;         const bool lvalid = (bk & 15) != 0, rvalid = (bk & 15) != 15;
; #pragma unroll
;         for (int bj = 0; bj < 2; ++bj) {
;             const unsigned colp = u.pn * 256 + bj * 128 + wc * 32 + 8 * fq;
;             const unsigned coll = bj * FF + u.pn * 128 + wc * 32 + 8 * fq;
; #pragma unroll
;             for (int n = 0; n < 2; ++n) {
;                 f32x4 c0 = ldf4(cw, coll + 4u * n), c1 = ldf4(cw, (unsigned)FF2 + coll + 4u * n), c2 = ldf4(cw, 2u * FF2 + coll + 4u * n);
;                 if constexpr (I8) { const f32x4 swv = ldf4(sw, colp + 4u * n); c0 = c0 * swv; c1 = c1 * swv; c2 = c2 * swv; }
;                 f32x4 hl = {0.f, 0.f, 0.f, 0.f}, hr = {0.f, 0.f, 0.f, 0.f};
;                 if (fr == 0 && lvalid) hl = ldf4(HALO, (2u * bk) * (unsigned)FF2 + colp + 4u * n);
;                 if (fr == 15 && rvalid) hr = ldf4(HALO, (2u * bk + 1u) * (unsigned)FF2 + colp + 4u * n);
; #pragma unroll
;                 for (int e = 0; e < 4; ++e) {
;                     const float prev = dpp_shr1(hl[e], acc[1][bj][3][n][e]);
;                     const float next = dpp_shl1(hr[e], acc[0][bj][0][n][e]);
.Lzs_1:
	s_and_saveexec_b64 s[60:61], vcc
	v_mov_b32_e32 v124, v224
	v_mov_b32_e32 v125, v225
	v_mov_b32_e32 v126, v226
	v_mov_b32_e32 v127, v227
.LBB0_1072:
	s_or_b64 exec, exec, s[60:61]
	s_cmp_lg_u64 s[44:45], 0
	s_cbranch_scc1 .Lzs_4e
	v_mov_b32_e32 v184, 0
	v_mov_b32_e32 v185, 0
	v_mov_b32_e32 v186, 0
	v_mov_b32_e32 v187, 0
.Lzs_4e:
	s_and_saveexec_b64 s[60:61], s[44:45]
	v_mov_b32_e32 v184, v228
	v_mov_b32_e32 v185, v229
	v_mov_b32_e32 v186, v230
	v_mov_b32_e32 v187, v231
	s_or_b64 exec, exec, s[60:61]
	s_cbranch_vccnz .Lzs_5e
	v_mov_b32_e32 v204, 0
	v_mov_b32_e32 v205, 0
	v_mov_b32_e32 v206, 0
	v_mov_b32_e32 v207, 0
.Lzs_5e:
	s_and_saveexec_b64 s[60:61], vcc
	v_mov_b32_e32 v204, v232
	v_mov_b32_e32 v205, v233
	v_mov_b32_e32 v206, v234
	v_mov_b32_e32 v207, v235
	s_or_b64 exec, exec, s[60:61]
	v_mov_b32_e32 v147, v209
	v_lshl_add_u64 v[180:181], s[28:29], 0, v[146:147]
	v_cvt_f32_i32_e32 v147, v161
	v_cvt_f32_i32_e32 v146, v160
	v_cvt_f32_i32_e32 v161, v163
	v_cvt_f32_i32_e32 v160, v162
	v_lshl_add_u64 v[164:165], s[22:23], 0, v[208:209]
	v_cvt_f32_i32_e32 v149, v149
	v_cvt_f32_i32_e32 v148, v148
	v_cvt_f32_i32_e32 v153, v153
	v_cvt_f32_i32_e32 v152, v152
	v_cvt_f32_i32_e32 v155, v155
	v_cvt_f32_i32_e32 v154, v154
	v_cvt_f32_i32_e32 v151, v151
	v_cvt_f32_i32_e32 v150, v150
	v_cvt_f32_i32_e32 v117, v117
	v_cvt_f32_i32_e32 v116, v116
	v_cvt_f32_i32_e32 v109, v109
	v_cvt_f32_i32_e32 v108, v108
	v_cvt_f32_i32_e32 v119, v119
	v_cvt_f32_i32_e32 v118, v118
	v_cvt_f32_i32_e32 v111, v111
	v_cvt_f32_i32_e32 v110, v110
	v_cvt_f32_i32_e32 v53, v53
	v_cvt_f32_i32_e32 v52, v52
	v_cvt_f32_i32_e32 v49, v49
	v_cvt_f32_i32_e32 v48, v48
	v_cvt_f32_i32_e32 v45, v45
	v_cvt_f32_i32_e32 v44, v44
	v_cvt_f32_i32_e32 v41, v41
	v_cvt_f32_i32_e32 v40, v40
	v_cvt_f32_i32_e32 v37, v37
	v_cvt_f32_i32_e32 v36, v36
	v_cvt_f32_i32_e32 v33, v33
	v_cvt_f32_i32_e32 v32, v32
	v_cvt_f32_i32_e32 v55, v55
	v_cvt_f32_i32_e32 v54, v54
	v_cvt_f32_i32_e32 v51, v51
	v_cvt_f32_i32_e32 v50, v50
	v_cvt_f32_i32_e32 v47, v47
	v_cvt_f32_i32_e32 v46, v46
	v_cvt_f32_i32_e32 v43, v43
	v_cvt_f32_i32_e32 v42, v42
	v_cvt_f32_i32_e32 v39, v39
	v_cvt_f32_i32_e32 v38, v38
	v_cvt_f32_i32_e32 v27, v27
	v_cvt_f32_i32_e32 v26, v26
	v_cvt_f32_i32_e32 v13, v13
	v_cvt_f32_i32_e32 v12, v12
	v_cvt_f32_i32_e32 v35, v35
	v_cvt_f32_i32_e32 v34, v34
	v_cvt_f32_i32_e32 v101, v101
	v_cvt_f32_i32_e32 v100, v100
	v_cvt_f32_i32_e32 v97, v97
	v_cvt_f32_i32_e32 v96, v96
	v_cvt_f32_i32_e32 v93, v93
	v_cvt_f32_i32_e32 v92, v92
	v_cvt_f32_i32_e32 v11, v11
	v_cvt_f32_i32_e32 v10, v10
	v_cvt_f32_i32_e32 v89, v89
	v_cvt_f32_i32_e32 v88, v88
	v_cvt_f32_i32_e32 v31, v31
	v_cvt_f32_i32_e32 v30, v30
	v_cvt_f32_i32_e32 v17, v17
	v_cvt_f32_i32_e32 v16, v16
	v_cvt_f32_i32_e32 v85, v85
	v_cvt_f32_i32_e32 v84, v84
	v_cvt_f32_i32_e32 v77, v77
	v_cvt_f32_i32_e32 v79, v79
	v_cvt_f32_i32_e32 v78, v78
	v_cvt_f32_i32_e32 v76, v76
	v_cvt_f32_i32_e32 v57, v57
	v_cvt_f32_i32_e32 v59, v59
	v_cvt_f32_i32_e32 v58, v58
	v_cvt_f32_i32_e32 v56, v56
	v_cvt_f32_i32_e32 v7, v7
	v_cvt_f32_i32_e32 v6, v6
	v_cvt_f32_i32_e32 v103, v103
	v_cvt_f32_i32_e32 v102, v102
	v_cvt_f32_i32_e32 v99, v99
	v_cvt_f32_i32_e32 v98, v98
	v_cvt_f32_i32_e32 v95, v95
	v_cvt_f32_i32_e32 v94, v94
	v_cvt_f32_i32_e32 v91, v91
	v_cvt_f32_i32_e32 v90, v90
	v_cvt_f32_i32_e32 v87, v87
	v_cvt_f32_i32_e32 v86, v86
	v_cvt_f32_i32_e32 v81, v81
	v_cvt_f32_i32_e32 v80, v80
	v_cvt_f32_i32_e32 v73, v73
	v_cvt_f32_i32_e32 v72, v72
	v_cvt_f32_i32_e32 v69, v69
	v_cvt_f32_i32_e32 v68, v68
	v_cvt_f32_i32_e32 v65, v65
	v_cvt_f32_i32_e32 v64, v64
	v_cvt_f32_i32_e32 v61, v61
	v_cvt_f32_i32_e32 v60, v60
	v_cvt_f32_i32_e32 v83, v83
	v_cvt_f32_i32_e32 v82, v82
	v_cvt_f32_i32_e32 v67, v67
	v_cvt_f32_i32_e32 v66, v66
	v_cvt_f32_i32_e32 v63, v63
	v_cvt_f32_i32_e32 v62, v62
	v_cvt_f32_i32_e32 v29, v29
	v_cvt_f32_i32_e32 v28, v28
	v_cvt_f32_i32_e32 v25, v25
	v_cvt_f32_i32_e32 v24, v24
	v_cvt_f32_i32_e32 v19, v19
	v_cvt_f32_i32_e32 v18, v18
	v_cvt_f32_i32_e32 v15, v15
	v_cvt_f32_i32_e32 v14, v14
	v_cvt_f32_i32_e32 v75, v75
	v_cvt_f32_i32_e32 v74, v74
	v_cvt_f32_i32_e32 v23, v23
	v_cvt_f32_i32_e32 v22, v22
	v_cvt_f32_i32_e32 v21, v21
	v_cvt_f32_i32_e32 v20, v20
	v_cvt_f32_i32_e32 v71, v71
	v_cvt_f32_i32_e32 v70, v70
	s_waitcnt vmcnt(3)
	v_pk_mul_f32 v[224:225], v[112:113], v[146:147] op_sel_hi:[0,1]
	v_cvt_f32_i32_e32 v147, v157
	v_cvt_f32_i32_e32 v146, v156
	v_cvt_f32_i32_e32 v157, v159
	v_cvt_f32_i32_e32 v156, v158
	s_waitcnt vmcnt(2)
	v_mov_b32_e32 v158, v107
	v_add_u32_e32 v145, 0xb010, v208
	v_pk_mul_f32 v[220:221], v[112:113], v[160:161] op_sel_hi:[0,1]
	v_pk_mul_f32 v[218:219], v[158:159], v[156:157] op_sel_hi:[0,1]
	v_pk_mul_f32 v[222:223], v[158:159], v[146:147] op_sel_hi:[0,1]
	global_load_dwordx4 v[160:163], v[164:165], off offset:16
	global_load_dwordx4 v[156:159], v145, s[22:23]
	v_add_u32_e32 v145, 0x16010, v208
	global_load_dwordx4 v[164:167], v145, s[22:23]
	global_load_dwordx4 v[168:171], v[180:181], off offset:16
	s_waitcnt vmcnt(4)
	v_mov_b32_dpp v120, v222 row_shr:1 row_mask:0xf bank_mask:0xf
	v_mov_b32_dpp v124, v224 row_shl:1 row_mask:0xf bank_mask:0xf
	v_mov_b32_dpp v121, v223 row_shr:1 row_mask:0xf bank_mask:0xf
	v_mov_b32_dpp v125, v225 row_shl:1 row_mask:0xf bank_mask:0xf
	v_mov_b32_dpp v122, v218 row_shr:1 row_mask:0xf bank_mask:0xf
	v_mov_b32_dpp v126, v220 row_shl:1 row_mask:0xf bank_mask:0xf
	v_mov_b32_dpp v123, v219 row_shr:1 row_mask:0xf bank_mask:0xf
	v_mov_b32_dpp v127, v221 row_shl:1 row_mask:0xf bank_mask:0xf
	s_cmp_lg_u64 s[44:45], 0
	s_cbranch_scc1 .Lzs_2
	v_mov_b32_e32 v145, 0
	v_mov_b32_e32 v146, 0
	v_mov_b32_e32 v147, 0

;     __device__ bool next(int i, Unit& u) const { return S.next(i, u); }
;     __device__ bool next(int i, Unit& u) const { const int L = i * G + c; if (L >= 3 * 44) return false; u.pm = L % 3; u.pn = L / 3; u.g = 0; u.part = 0; u.keep = 0; return true; }
;     __device__ __forceinline__ void operator()(Acc& acc, const Unit& u, int wr, int wc, int fr, int fq, LAS unsigned char* lds, int tid) const {
;     ...
;                 f32x4 c0 = ldf4(cw, coll + 4u * n), c1 = ldf4(cw, (unsigned)FF2 + coll + 4u * n), c2 = ldf4(cw, 2u * FF2 + coll + 4u * n);
;                 if constexpr (I8) { const f32x4 swv = ldf4(sw, colp + 4u * n); c0 = c0 * swv; c1 = c1 * swv; c2 = c2 * swv; }
;                 f32x4 hl = {0.f, 0.f, 0.f, 0.f}, hr = {0.f, 0.f, 0.f, 0.f};
;                 if (fr == 0 && lvalid) hl = ldf4(HALO, (2u * bk) * (unsigned)FF2 + colp + 4u * n);
;                 if (fr == 15 && rvalid) hr = ldf4(HALO, (2u * bk + 1u) * (unsigned)FF2 + colp + 4u * n);
; #pragma unroll
;                 for (int e = 0; e < 4; ++e) {
;                     const float prev = dpp_shr1(hl[e], acc[1][bj][3][n][e]);
;                     const float next = dpp_shl1(hr[e], acc[0][bj][0][n][e]);
;                     float left = prev;
; #pragma unroll
;                     for (int j = 0; j < 8; ++j) {
;                         const float cur = acc[j >> 2][bj][j & 3][n][e];
;                         const float nx = (j < 7) ? acc[(j + 1) >> 2][bj][(j + 1) & 3][n][e] : next;
;                         acc[j >> 2][bj][j & 3][n][e] = c0[e] * left + c1[e] * cur + c2[e] * nx;
;                         left = cur;
;                     }
.LBB0_1076:
	s_or_b64 exec, exec, s[60:61]
	v_mov_b32_e32 v226, v107
	v_mov_b32_e32 v227, v107
	v_pk_mul_f32 v[234:235], v[226:227], v[148:149]
	v_add_u32_e32 v149, 0x5800, v208
	global_load_dwordx4 v[188:191], v149, s[22:23]
	v_add_u32_e32 v149, 0x10800, v208
	v_or_b32_e32 v148, 0x80, v177
	global_load_dwordx4 v[196:199], v149, s[22:23]
	v_add_u32_e32 v149, 0x1b800, v208
	global_load_dwordx4 v[192:195], v149, s[22:23]
	v_lshlrev_b32_e32 v149, 2, v148
	global_load_dwordx4 v[200:203], v149, s[28:29]
	v_mov_b32_e32 v228, v112
	v_mov_b32_e32 v229, v112
	v_mov_b32_e32 v178, v112
	v_mov_b32_e32 v179, v112
	v_pk_mul_f32 v[236:237], v[228:229], v[152:153]
	v_mov_b32_e32 v152, v107
	v_mov_b32_e32 v153, v107
	v_pk_mul_f32 v[232:233], v[178:179], v[154:155]
	v_pk_mul_f32 v[230:231], v[152:153], v[150:151]
	s_waitcnt vmcnt(4)
	v_mov_b32_dpp v144, v234 row_shr:1 row_mask:0xf bank_mask:0xf
	v_mov_b32_dpp v172, v236 row_shl:1 row_mask:0xf bank_mask:0xf
	v_mov_b32_dpp v145, v235 row_shr:1 row_mask:0xf bank_mask:0xf
	v_mov_b32_dpp v173, v237 row_shl:1 row_mask:0xf bank_mask:0xf
	v_mov_b32_dpp v146, v230 row_shr:1 row_mask:0xf bank_mask:0xf
	v_mov_b32_dpp v174, v232 row_shl:1 row_mask:0xf bank_mask:0xf
	v_mov_b32_dpp v147, v231 row_shr:1 row_mask:0xf bank_mask:0xf
	v_mov_b32_dpp v175, v233 row_shl:1 row_mask:0xf bank_mask:0xf
	v_add_u32_e32 v215, s1, v148
	v_add_u32_e32 v216, s0, v148
	v_mov_b32_e32 v148, 0
	v_mov_b32_e32 v150, v112
	v_mov_b32_e32 v151, v112
	v_pk_mul_f32 v[244:245], v[228:229], v[116:117]
	v_mov_b32_e32 v116, v107
	v_mov_b32_e32 v117, v107
	v_pk_mul_f32 v[242:243], v[226:227], v[108:109]
	v_add_u32_e32 v108, 0x5810, v208
	v_pk_mul_f32 v[240:241], v[150:151], v[118:119]
	v_pk_mul_f32 v[238:239], v[116:117], v[110:111]
	v_mov_b32_e32 v176, v184
	v_mov_b32_e32 v177, v185
	v_mov_b32_e32 v178, v186
	v_mov_b32_e32 v179, v187
	global_load_dwordx4 v[116:119], v108, s[22:23]
	v_add_u32_e32 v108, 0x10810, v208
	global_load_dwordx4 v[184:187], v108, s[22:23]
	v_add_u32_e32 v108, 0x1b810, v208
	global_load_dwordx4 v[152:155], v108, s[22:23]
	s_nop 0
	global_load_dwordx4 v[180:183], v[180:181], off offset:528
	s_waitcnt vmcnt(4)
	v_mov_b32_dpp v176, v242 row_shr:1 row_mask:0xf bank_mask:0xf
	v_mov_b32_dpp v204, v244 row_shl:1 row_mask:0xf bank_mask:0xf
	v_mov_b32_dpp v177, v243 row_shr:1 row_mask:0xf bank_mask:0xf
	v_mov_b32_dpp v205, v245 row_shl:1 row_mask:0xf bank_mask:0xf
	v_mov_b32_dpp v178, v238 row_shr:1 row_mask:0xf bank_mask:0xf
	v_mov_b32_dpp v206, v240 row_shl:1 row_mask:0xf bank_mask:0xf
	v_mov_b32_dpp v179, v239 row_shr:1 row_mask:0xf bank_mask:0xf
	v_mov_b32_dpp v207, v241 row_shl:1 row_mask:0xf bank_mask:0xf
	s_cmp_lg_u64 s[44:45], 0
	s_cbranch_scc1 .Lzs_6
	v_mov_b32_e32 v149, 0
	v_mov_b32_e32 v150, 0
	v_mov_b32_e32 v151, 0
